# v81 + K-loop head placement: A and F loops at 4 mod 8, E/H/I loops at 0 mod 8
# baseline (speedup 1.0000x reference)
.LBB0_266:
	s_xor_b64 s[2:3], s[2:3], -1
	s_mov_b32 s34, s74
	s_add_i32 s74, s74, 1
	s_cmp_lt_u32 s34, 5
	s_mov_b64 s[4:5], s[10:11]
	s_mov_b32 s10, s75
	s_cselect_b64 s[14:15], -1, 0
	s_add_i32 s75, s74, s16
	s_mov_b64 s[12:13], s[8:9]
	s_and_b64 s[8:9], s[14:15], exec
	s_cselect_b32 s8, s75, s10
	s_cselect_b32 s10, s6, s6
	s_ashr_i32 s11, s10, 31
	s_lshl_b64 s[10:11], s[10:11], 19
	s_add_u32 s10, s80, s10
	s_addc_u32 s11, s81, s11
	s_and_b64 s[44:45], s[14:15], exec
	s_cselect_b32 s44, s11, s5
	s_cselect_b32 s45, s10, s4
	s_ashr_i32 s9, s8, 31
	s_lshl_b64 s[8:9], s[8:9], 19
	v_readlane_b32 s47, v255, 14
	s_add_u32 s8, s47, s8
	v_readlane_b32 s47, v255, 15
	s_addc_u32 s9, s47, s9
	s_and_b64 s[14:15], s[14:15], exec
	s_cselect_b32 s47, s9, s13
	s_cselect_b32 s55, s8, s12
	s_add_u32 s4, s4, 0x40080
	s_addc_u32 s5, s5, 0
	s_add_u32 s78, s12, 0x100
	s_addc_u32 s79, s13, 0
	s_mov_b32 s85, -2
	s_waitcnt lgkmcnt(0)
	s_add_i32 s86, 0, 0x10000
	v_add_u32_e32 v0, s86, v150
	v_add_u32_e32 v189, 0x10000, v150
	ds_read_b128 v[142:145], v0
	ds_read_b128 v[146:149], v0 offset:1024
	ds_read_b128 v[152:155], v0 offset:2048
	ds_read_b128 v[156:159], v0 offset:3072
	s_add_u32 s12, s4, 0xfffc0080
	s_addc_u32 s13, s5, -1
	s_cmp_eq_u32 s85, 12
	s_cselect_b32 s15, s44, s13
	s_cselect_b32 s14, s45, s12
	s_cselect_b32 s13, s47, s79
	s_cselect_b32 s12, s55, s78
	s_add_i32 m0, s7, 0xc000
	ds_read_b128 v[160:163], v151
	ds_read_b128 v[164:167], v151 offset:1024
	ds_read_b128 v[168:171], v151 offset:2048
	ds_read_b128 v[172:175], v151 offset:3072
	ds_read_b128 v[176:179], v151 offset:4096
	ds_read_b128 v[180:183], v151 offset:5120
	ds_read_b128 v[184:187], v151 offset:6144
	global_load_lds_dwordx4 v138, s[4:5]
	s_add_i32 m0, s7, 0xe000
	ds_read_b128 v[190:193], v151 offset:7168
	global_load_lds_dwordx4 v140, s[4:5]
	s_waitcnt lgkmcnt(8)
	s_barrier
	s_waitcnt lgkmcnt(0)
	v_mfma_f32_16x16x32_bf16 v[126:129], v[142:145], v[160:163], 0
	v_mfma_f32_16x16x32_bf16 v[122:125], v[152:155], v[160:163], 0
	v_mfma_f32_16x16x32_bf16 v[110:113], v[142:145], v[168:171], 0
	v_mfma_f32_16x16x32_bf16 v[106:109], v[152:155], v[168:171], 0
	v_mfma_f32_16x16x32_bf16 v[94:97], v[142:145], v[176:179], 0
	v_mfma_f32_16x16x32_bf16 v[90:93], v[152:155], v[176:179], 0
	v_mfma_f32_16x16x32_bf16 v[78:81], v[142:145], v[184:187], 0
	v_mfma_f32_16x16x32_bf16 v[74:77], v[152:155], v[184:187], 0
	v_mfma_f32_16x16x32_bf16 v[126:129], v[146:149], v[164:167], v[126:129]
	v_mfma_f32_16x16x32_bf16 v[122:125], v[156:159], v[164:167], v[122:125]
	v_mfma_f32_16x16x32_bf16 v[110:113], v[146:149], v[172:175], v[110:113]
	v_mfma_f32_16x16x32_bf16 v[106:109], v[156:159], v[172:175], v[106:109]
	v_mfma_f32_16x16x32_bf16 v[94:97], v[146:149], v[180:183], v[94:97]
	v_mfma_f32_16x16x32_bf16 v[90:93], v[156:159], v[180:183], v[90:93]
	v_mfma_f32_16x16x32_bf16 v[78:81], v[146:149], v[190:193], v[78:81]
	v_mfma_f32_16x16x32_bf16 v[74:77], v[156:159], v[190:193], v[74:77]
	s_barrier
	s_add_i32 m0, s22, 0x10000
	ds_read_b128 v[194:197], v189 offset:16384
	ds_read_b128 v[198:201], v189 offset:17408
	ds_read_b128 v[202:205], v189 offset:18432
	global_load_lds_dwordx4 v134, s[12:13]
	s_add_i32 m0, s22, 0x12000
	ds_read_b128 v[206:209], v189 offset:19456
	global_load_lds_dwordx4 v130, s[12:13]
	s_barrier
	s_waitcnt lgkmcnt(0)
	v_mfma_f32_16x16x32_bf16 v[118:121], v[194:197], v[160:163], 0
	v_mfma_f32_16x16x32_bf16 v[114:117], v[202:205], v[160:163], 0
	v_mfma_f32_16x16x32_bf16 v[102:105], v[194:197], v[168:171], 0
	v_mfma_f32_16x16x32_bf16 v[98:101], v[202:205], v[168:171], 0
	v_mfma_f32_16x16x32_bf16 v[86:89], v[194:197], v[176:179], 0
	v_mfma_f32_16x16x32_bf16 v[82:85], v[202:205], v[176:179], 0
	v_mfma_f32_16x16x32_bf16 v[70:73], v[194:197], v[184:187], 0
	v_mfma_f32_16x16x32_bf16 v[66:69], v[202:205], v[184:187], 0
	v_mfma_f32_16x16x32_bf16 v[118:121], v[198:201], v[164:167], v[118:121]
	v_mfma_f32_16x16x32_bf16 v[114:117], v[206:209], v[164:167], v[114:117]
	v_mfma_f32_16x16x32_bf16 v[102:105], v[198:201], v[172:175], v[102:105]
	v_mfma_f32_16x16x32_bf16 v[98:101], v[206:209], v[172:175], v[98:101]
	v_mfma_f32_16x16x32_bf16 v[86:89], v[198:201], v[180:183], v[86:89]
	v_mfma_f32_16x16x32_bf16 v[82:85], v[206:209], v[180:183], v[82:85]
	v_mfma_f32_16x16x32_bf16 v[70:73], v[198:201], v[190:193], v[70:73]
	v_mfma_f32_16x16x32_bf16 v[66:69], v[206:209], v[190:193], v[66:69]
	s_mov_b32 m0, s7
	s_mov_b64 s[100:101], s[14:15]
	s_barrier
	ds_read_b128 v[160:163], v151 offset:16384
	ds_read_b128 v[164:167], v151 offset:17408
	ds_read_b128 v[168:171], v151 offset:18432
	ds_read_b128 v[172:175], v151 offset:19456
	ds_read_b128 v[176:179], v151 offset:20480
	ds_read_b128 v[180:183], v151 offset:21504
	ds_read_b128 v[184:187], v151 offset:22528
	global_load_lds_dwordx4 v136, s[100:101]
	s_mov_b32 m0, s23
	ds_read_b128 v[190:193], v151 offset:23552
	global_load_lds_dwordx4 v132, s[100:101]
	s_waitcnt vmcnt(10)
	s_barrier
	s_waitcnt lgkmcnt(0)
	v_mfma_f32_16x16x32_bf16 v[62:65], v[142:145], v[160:163], 0
	v_mfma_f32_16x16x32_bf16 v[58:61], v[152:155], v[160:163], 0
	v_mfma_f32_16x16x32_bf16 v[46:49], v[142:145], v[168:171], 0
	v_mfma_f32_16x16x32_bf16 v[42:45], v[152:155], v[168:171], 0
	v_mfma_f32_16x16x32_bf16 v[30:33], v[142:145], v[176:179], 0
	v_mfma_f32_16x16x32_bf16 v[26:29], v[152:155], v[176:179], 0
	v_mfma_f32_16x16x32_bf16 v[14:17], v[142:145], v[184:187], 0
	v_mfma_f32_16x16x32_bf16 v[10:13], v[152:155], v[184:187], 0
	v_mfma_f32_16x16x32_bf16 v[62:65], v[146:149], v[164:167], v[62:65]
	v_mfma_f32_16x16x32_bf16 v[58:61], v[156:159], v[164:167], v[58:61]
	v_mfma_f32_16x16x32_bf16 v[46:49], v[146:149], v[172:175], v[46:49]
	v_mfma_f32_16x16x32_bf16 v[42:45], v[156:159], v[172:175], v[42:45]
	v_mfma_f32_16x16x32_bf16 v[30:33], v[146:149], v[180:183], v[30:33]
	v_mfma_f32_16x16x32_bf16 v[26:29], v[156:159], v[180:183], v[26:29]
	v_mfma_f32_16x16x32_bf16 v[14:17], v[146:149], v[190:193], v[14:17]
	v_mfma_f32_16x16x32_bf16 v[10:13], v[156:159], v[190:193], v[10:13]
	s_barrier
	s_add_u32 s86, s12, 0x40000
	s_addc_u32 s87, s13, 0
	s_add_i32 m0, s22, 0x14000
	s_nop 0
	global_load_lds_dwordx4 v134, s[86:87]
	s_add_i32 m0, s22, 0x16000
	s_nop 0
	global_load_lds_dwordx4 v130, s[86:87]
	ds_read_b128 v[142:145], v189 offset:32768
	ds_read_b128 v[146:149], v189 offset:33792
	ds_read_b128 v[152:155], v189 offset:34816
	ds_read_b128 v[156:159], v189 offset:35840
	s_waitcnt vmcnt(6)
	s_barrier
	v_mfma_f32_16x16x32_bf16 v[54:57], v[194:197], v[160:163], 0
	v_mfma_f32_16x16x32_bf16 v[50:53], v[202:205], v[160:163], 0
	v_mfma_f32_16x16x32_bf16 v[38:41], v[194:197], v[168:171], 0
	v_mfma_f32_16x16x32_bf16 v[34:37], v[202:205], v[168:171], 0
	v_mfma_f32_16x16x32_bf16 v[22:25], v[194:197], v[176:179], 0
	v_mfma_f32_16x16x32_bf16 v[18:21], v[202:205], v[176:179], 0
	v_mfma_f32_16x16x32_bf16 v[6:9], v[194:197], v[184:187], 0
	v_mfma_f32_16x16x32_bf16 v[2:5], v[202:205], v[184:187], 0
	v_mfma_f32_16x16x32_bf16 v[54:57], v[198:201], v[164:167], v[54:57]
	v_mfma_f32_16x16x32_bf16 v[50:53], v[206:209], v[164:167], v[50:53]
	v_mfma_f32_16x16x32_bf16 v[38:41], v[198:201], v[172:175], v[38:41]
	v_mfma_f32_16x16x32_bf16 v[34:37], v[206:209], v[172:175], v[34:37]
	v_mfma_f32_16x16x32_bf16 v[22:25], v[198:201], v[180:183], v[22:25]
	v_mfma_f32_16x16x32_bf16 v[18:21], v[206:209], v[180:183], v[18:21]
	v_mfma_f32_16x16x32_bf16 v[6:9], v[198:201], v[190:193], v[6:9]
	v_mfma_f32_16x16x32_bf16 v[2:5], v[206:209], v[190:193], v[2:5]
	s_barrier
	s_add_u32 s14, s14, 0x40000
	s_addc_u32 s15, s15, 0
	s_mov_b32 m0, s28
	ds_read_b128 v[160:163], v151 offset:32768
	ds_read_b128 v[164:167], v151 offset:33792
	ds_read_b128 v[168:171], v151 offset:34816
	ds_read_b128 v[172:175], v151 offset:35840
	ds_read_b128 v[176:179], v151 offset:36864
	ds_read_b128 v[180:183], v151 offset:37888
	ds_read_b128 v[184:187], v151 offset:38912
	global_load_lds_dwordx4 v136, s[14:15]
	s_mov_b32 m0, s29
	ds_read_b128 v[190:193], v151 offset:39936
	global_load_lds_dwordx4 v132, s[14:15]
	s_waitcnt lgkmcnt(8)
	s_barrier
	s_waitcnt lgkmcnt(0)
	v_mfma_f32_16x16x32_bf16 v[126:129], v[142:145], v[160:163], v[126:129]
	v_mfma_f32_16x16x32_bf16 v[122:125], v[152:155], v[160:163], v[122:125]
	v_mfma_f32_16x16x32_bf16 v[110:113], v[142:145], v[168:171], v[110:113]
	v_mfma_f32_16x16x32_bf16 v[106:109], v[152:155], v[168:171], v[106:109]
	v_mfma_f32_16x16x32_bf16 v[94:97], v[142:145], v[176:179], v[94:97]
	v_mfma_f32_16x16x32_bf16 v[90:93], v[152:155], v[176:179], v[90:93]
	v_mfma_f32_16x16x32_bf16 v[78:81], v[142:145], v[184:187], v[78:81]
	v_mfma_f32_16x16x32_bf16 v[74:77], v[152:155], v[184:187], v[74:77]
	v_mfma_f32_16x16x32_bf16 v[126:129], v[146:149], v[164:167], v[126:129]
	v_mfma_f32_16x16x32_bf16 v[122:125], v[156:159], v[164:167], v[122:125]
	v_mfma_f32_16x16x32_bf16 v[110:113], v[146:149], v[172:175], v[110:113]
	v_mfma_f32_16x16x32_bf16 v[106:109], v[156:159], v[172:175], v[106:109]
	v_mfma_f32_16x16x32_bf16 v[94:97], v[146:149], v[180:183], v[94:97]
	v_mfma_f32_16x16x32_bf16 v[90:93], v[156:159], v[180:183], v[90:93]
	v_mfma_f32_16x16x32_bf16 v[78:81], v[146:149], v[190:193], v[78:81]
	v_mfma_f32_16x16x32_bf16 v[74:77], v[156:159], v[190:193], v[74:77]
	s_barrier
	s_add_i32 m0, s22, 0x18000
	ds_read_b128 v[194:197], v189 offset:49152
	ds_read_b128 v[198:201], v189 offset:50176
	ds_read_b128 v[202:205], v189 offset:51200
	ds_read_b128 v[206:209], v189 offset:52224
	s_add_u32 s98, s12, s40
	s_addc_u32 s99, s13, s41
	global_load_lds_dwordx4 v134, s[98:99]
	s_add_i32 m0, s22, 0x1a000
	s_nop 0
	global_load_lds_dwordx4 v130, s[98:99]
	s_barrier
	s_waitcnt lgkmcnt(0)
	v_mfma_f32_16x16x32_bf16 v[118:121], v[194:197], v[160:163], v[118:121]
	v_mfma_f32_16x16x32_bf16 v[114:117], v[202:205], v[160:163], v[114:117]
	v_mfma_f32_16x16x32_bf16 v[102:105], v[194:197], v[168:171], v[102:105]
	v_mfma_f32_16x16x32_bf16 v[98:101], v[202:205], v[168:171], v[98:101]
	v_mfma_f32_16x16x32_bf16 v[86:89], v[194:197], v[176:179], v[86:89]
	v_mfma_f32_16x16x32_bf16 v[82:85], v[202:205], v[176:179], v[82:85]
	v_mfma_f32_16x16x32_bf16 v[70:73], v[194:197], v[184:187], v[70:73]
	v_mfma_f32_16x16x32_bf16 v[66:69], v[202:205], v[184:187], v[66:69]
	v_mfma_f32_16x16x32_bf16 v[118:121], v[198:201], v[164:167], v[118:121]
	v_mfma_f32_16x16x32_bf16 v[114:117], v[206:209], v[164:167], v[114:117]
	v_mfma_f32_16x16x32_bf16 v[102:105], v[198:201], v[172:175], v[102:105]
	v_mfma_f32_16x16x32_bf16 v[98:101], v[206:209], v[172:175], v[98:101]
	v_mfma_f32_16x16x32_bf16 v[86:89], v[198:201], v[180:183], v[86:89]
	v_mfma_f32_16x16x32_bf16 v[82:85], v[206:209], v[180:183], v[82:85]
	v_mfma_f32_16x16x32_bf16 v[70:73], v[198:201], v[190:193], v[70:73]
	v_mfma_f32_16x16x32_bf16 v[66:69], v[206:209], v[190:193], v[66:69]
	s_mov_b32 m0, s38
	s_barrier
	ds_read_b128 v[160:163], v151 offset:49152
	ds_read_b128 v[164:167], v151 offset:50176
	ds_read_b128 v[168:171], v151 offset:51200
	ds_read_b128 v[172:175], v151 offset:52224
	ds_read_b128 v[176:179], v151 offset:53248
	ds_read_b128 v[180:183], v151 offset:54272
	ds_read_b128 v[184:187], v151 offset:55296
	ds_read_b128 v[190:193], v151 offset:56320
	s_add_u32 s98, s100, s40
	s_addc_u32 s99, s101, s41
	global_load_lds_dwordx4 v136, s[98:99]
	s_mov_b32 m0, s39
	s_nop 0
	global_load_lds_dwordx4 v132, s[98:99]
	s_waitcnt vmcnt(10)
	s_barrier
	s_waitcnt lgkmcnt(0)
	v_mfma_f32_16x16x32_bf16 v[62:65], v[142:145], v[160:163], v[62:65]
	v_mfma_f32_16x16x32_bf16 v[58:61], v[152:155], v[160:163], v[58:61]
	v_mfma_f32_16x16x32_bf16 v[46:49], v[142:145], v[168:171], v[46:49]
	v_mfma_f32_16x16x32_bf16 v[42:45], v[152:155], v[168:171], v[42:45]
	v_mfma_f32_16x16x32_bf16 v[30:33], v[142:145], v[176:179], v[30:33]
	v_mfma_f32_16x16x32_bf16 v[26:29], v[152:155], v[176:179], v[26:29]
	v_mfma_f32_16x16x32_bf16 v[14:17], v[142:145], v[184:187], v[14:17]
	v_mfma_f32_16x16x32_bf16 v[10:13], v[152:155], v[184:187], v[10:13]
	v_mfma_f32_16x16x32_bf16 v[62:65], v[146:149], v[164:167], v[62:65]
	v_mfma_f32_16x16x32_bf16 v[58:61], v[156:159], v[164:167], v[58:61]
	v_mfma_f32_16x16x32_bf16 v[46:49], v[146:149], v[172:175], v[46:49]
	v_mfma_f32_16x16x32_bf16 v[42:45], v[156:159], v[172:175], v[42:45]
	v_mfma_f32_16x16x32_bf16 v[30:33], v[146:149], v[180:183], v[30:33]
	v_mfma_f32_16x16x32_bf16 v[26:29], v[156:159], v[180:183], v[26:29]
	v_mfma_f32_16x16x32_bf16 v[14:17], v[146:149], v[190:193], v[14:17]
	v_mfma_f32_16x16x32_bf16 v[10:13], v[156:159], v[190:193], v[10:13]
	s_barrier
	s_add_u32 s12, s12, 0x40080
	s_addc_u32 s13, s13, 0
	s_add_i32 m0, s22, 0x1c000
	s_nop 0
	global_load_lds_dwordx4 v134, s[12:13]
	s_add_i32 m0, s22, 0x1e000
	s_nop 0
	global_load_lds_dwordx4 v130, s[12:13]
	ds_read_b128 v[142:145], v189
	ds_read_b128 v[146:149], v189 offset:1024
	ds_read_b128 v[152:155], v189 offset:2048
	ds_read_b128 v[156:159], v189 offset:3072
	s_waitcnt vmcnt(6)
	s_barrier
	v_mfma_f32_16x16x32_bf16 v[54:57], v[194:197], v[160:163], v[54:57]
	v_mfma_f32_16x16x32_bf16 v[50:53], v[202:205], v[160:163], v[50:53]
	v_mfma_f32_16x16x32_bf16 v[38:41], v[194:197], v[168:171], v[38:41]
	v_mfma_f32_16x16x32_bf16 v[34:37], v[202:205], v[168:171], v[34:37]
	v_mfma_f32_16x16x32_bf16 v[22:25], v[194:197], v[176:179], v[22:25]
	v_mfma_f32_16x16x32_bf16 v[18:21], v[202:205], v[176:179], v[18:21]
	v_mfma_f32_16x16x32_bf16 v[6:9], v[194:197], v[184:187], v[6:9]
	v_mfma_f32_16x16x32_bf16 v[2:5], v[202:205], v[184:187], v[2:5]
	v_mfma_f32_16x16x32_bf16 v[54:57], v[198:201], v[164:167], v[54:57]
	v_mfma_f32_16x16x32_bf16 v[50:53], v[206:209], v[164:167], v[50:53]
	v_mfma_f32_16x16x32_bf16 v[38:41], v[198:201], v[172:175], v[38:41]
	v_mfma_f32_16x16x32_bf16 v[34:37], v[206:209], v[172:175], v[34:37]
	v_mfma_f32_16x16x32_bf16 v[22:25], v[198:201], v[180:183], v[22:25]
	v_mfma_f32_16x16x32_bf16 v[18:21], v[206:209], v[180:183], v[18:21]
	v_mfma_f32_16x16x32_bf16 v[6:9], v[198:201], v[190:193], v[6:9]
	v_mfma_f32_16x16x32_bf16 v[2:5], v[206:209], v[190:193], v[2:5]
	s_add_i32 s85, s85, 2
	s_add_u32 s4, s4, 0x100
	s_addc_u32 s5, s5, 0
	s_add_u32 s78, s78, 0x100
	s_addc_u32 s79, s79, 0
	s_add_u32 s12, s4, 0xfffc0080
	s_addc_u32 s13, s5, -1
	s_cmp_eq_u32 s85, 12
	s_cselect_b32 s15, s44, s13
	s_cselect_b32 s14, s45, s12
	s_cselect_b32 s13, s47, s79
	s_cselect_b32 s12, s55, s78
	s_cmp_gt_u32 s85, 13
	s_barrier
	.p2align 3
	s_nop 0

.LBB0_918:
	s_ashr_i32 s17, s16, 31
	s_lshl_b64 s[22:23], s[16:17], 19
	v_mov_b64_e32 v[2:3], 0xb00
	s_add_u32 s84, s8, s22
	v_cmp_lt_i64_e32 vcc, s[28:29], v[2:3]
	s_addc_u32 s85, s9, s23
	s_and_b64 s[22:23], vcc, exec
	s_cselect_b32 s17, s85, s7
	s_cselect_b32 s22, s84, s6
	s_ashr_i32 s15, s14, 31
	s_lshl_b64 s[28:29], s[14:15], 19
	s_add_u32 s86, s37, s28
	s_addc_u32 s87, s38, s29
	s_and_b64 s[28:29], vcc, exec
	s_cselect_b32 s15, s87, s89
	s_cselect_b32 s23, s86, s88
	s_add_u32 s28, s88, 0x100
	s_addc_u32 s29, s89, 0
	s_mov_b32 s45, -2
	s_add_i32 vcc_lo, 0, 0x10000
	v_add_u32_e32 v0, vcc_lo, v254
	v_add_u32_e32 v189, 0x10000, v254
	ds_read_b128 v[130:133], v0
	ds_read_b128 v[134:137], v0 offset:1024
	ds_read_b128 v[138:141], v0 offset:2048
	ds_read_b128 v[142:145], v0 offset:3072
	s_add_u32 s88, s6, 0x100
	s_addc_u32 s89, s7, 0
	s_cmp_eq_u32 s45, 12
	s_cselect_b32 s93, s17, s89
	s_cselect_b32 s92, s22, s88
	s_cselect_b32 s91, s15, s29
	s_cselect_b32 s90, s23, s28
	s_add_i32 m0, s43, 0xc000
	ds_read_b128 v[146:149], v253
	ds_read_b128 v[150:153], v253 offset:1024
	ds_read_b128 v[168:171], v253 offset:2048
	ds_read_b128 v[172:175], v253 offset:3072
	ds_read_b128 v[176:179], v253 offset:4096
	ds_read_b128 v[180:183], v253 offset:5120
	ds_read_b128 v[184:187], v253 offset:6144
	ds_read_b128 v[190:193], v253 offset:7168
	global_load_lds_dwordx4 v164, s[6:7]
	s_add_i32 m0, s43, 0xe000
	v_lshl_add_u64 v[154:155], s[6:7], 0, v[166:167]
	global_load_lds_dwordx4 v[154:155], off
	s_waitcnt lgkmcnt(8)
	s_barrier
	s_waitcnt lgkmcnt(0)
	v_mfma_f32_16x16x32_bf16 v[126:129], v[130:133], v[146:149], 0
	v_mfma_f32_16x16x32_bf16 v[70:73], v[138:141], v[146:149], 0
	v_mfma_f32_16x16x32_bf16 v[122:125], v[130:133], v[168:171], 0
	v_mfma_f32_16x16x32_bf16 v[74:77], v[138:141], v[168:171], 0
	v_mfma_f32_16x16x32_bf16 v[114:117], v[130:133], v[176:179], 0
	v_mfma_f32_16x16x32_bf16 v[66:69], v[138:141], v[176:179], 0
	v_mfma_f32_16x16x32_bf16 v[110:113], v[130:133], v[184:187], 0
	v_mfma_f32_16x16x32_bf16 v[78:81], v[138:141], v[184:187], 0
	v_mfma_f32_16x16x32_bf16 v[126:129], v[134:137], v[150:153], v[126:129]
	v_mfma_f32_16x16x32_bf16 v[70:73], v[142:145], v[150:153], v[70:73]
	v_mfma_f32_16x16x32_bf16 v[122:125], v[134:137], v[172:175], v[122:125]
	v_mfma_f32_16x16x32_bf16 v[74:77], v[142:145], v[172:175], v[74:77]
	v_mfma_f32_16x16x32_bf16 v[114:117], v[134:137], v[180:183], v[114:117]
	v_mfma_f32_16x16x32_bf16 v[66:69], v[142:145], v[180:183], v[66:69]
	v_mfma_f32_16x16x32_bf16 v[110:113], v[134:137], v[190:193], v[110:113]
	v_mfma_f32_16x16x32_bf16 v[78:81], v[142:145], v[190:193], v[78:81]
	s_barrier
	s_add_i32 m0, s39, 0x10000
	ds_read_b128 v[194:197], v189 offset:16384
	ds_read_b128 v[198:201], v189 offset:17408
	ds_read_b128 v[202:205], v189 offset:18432
	global_load_lds_dwordx4 v160, s[90:91]
	s_add_i32 m0, s39, 0x12000
	ds_read_b128 v[206:209], v189 offset:19456
	global_load_lds_dwordx4 v156, s[90:91]
	s_barrier
	s_waitcnt lgkmcnt(0)
	v_mfma_f32_16x16x32_bf16 v[118:121], v[194:197], v[146:149], 0
	v_mfma_f32_16x16x32_bf16 v[94:97], v[202:205], v[146:149], 0
	v_mfma_f32_16x16x32_bf16 v[106:109], v[194:197], v[168:171], 0
	v_mfma_f32_16x16x32_bf16 v[90:93], v[202:205], v[168:171], 0
	v_mfma_f32_16x16x32_bf16 v[102:105], v[194:197], v[176:179], 0
	v_mfma_f32_16x16x32_bf16 v[82:85], v[202:205], v[176:179], 0
	v_mfma_f32_16x16x32_bf16 v[98:101], v[194:197], v[184:187], 0
	v_mfma_f32_16x16x32_bf16 v[86:89], v[202:205], v[184:187], 0
	v_mfma_f32_16x16x32_bf16 v[118:121], v[198:201], v[150:153], v[118:121]
	v_mfma_f32_16x16x32_bf16 v[94:97], v[206:209], v[150:153], v[94:97]
	v_mfma_f32_16x16x32_bf16 v[106:109], v[198:201], v[172:175], v[106:109]
	v_mfma_f32_16x16x32_bf16 v[90:93], v[206:209], v[172:175], v[90:93]
	v_mfma_f32_16x16x32_bf16 v[102:105], v[198:201], v[180:183], v[102:105]
	v_mfma_f32_16x16x32_bf16 v[82:85], v[206:209], v[180:183], v[82:85]
	v_mfma_f32_16x16x32_bf16 v[98:101], v[198:201], v[190:193], v[98:101]
	v_mfma_f32_16x16x32_bf16 v[86:89], v[206:209], v[190:193], v[86:89]
	s_mov_b32 m0, s43
	s_mov_b64 s[100:101], s[92:93]
	s_barrier
	ds_read_b128 v[146:149], v253 offset:16384
	ds_read_b128 v[150:153], v253 offset:17408
	ds_read_b128 v[168:171], v253 offset:18432
	ds_read_b128 v[172:175], v253 offset:19456
	ds_read_b128 v[176:179], v253 offset:20480
	ds_read_b128 v[180:183], v253 offset:21504
	ds_read_b128 v[184:187], v253 offset:22528
	global_load_lds_dwordx4 v162, s[100:101]
	s_mov_b32 m0, s60
	ds_read_b128 v[190:193], v253 offset:23552
	global_load_lds_dwordx4 v158, s[100:101]
	s_waitcnt vmcnt(10)
	s_barrier
	s_waitcnt lgkmcnt(0)
	v_mfma_f32_16x16x32_bf16 v[62:65], v[130:133], v[146:149], 0
	v_mfma_f32_16x16x32_bf16 v[10:13], v[138:141], v[146:149], 0
	v_mfma_f32_16x16x32_bf16 v[58:61], v[130:133], v[168:171], 0
	v_mfma_f32_16x16x32_bf16 v[14:17], v[138:141], v[168:171], 0
	v_mfma_f32_16x16x32_bf16 v[54:57], v[130:133], v[176:179], 0
	v_mfma_f32_16x16x32_bf16 v[6:9], v[138:141], v[176:179], 0
	v_mfma_f32_16x16x32_bf16 v[42:45], v[130:133], v[184:187], 0
	v_mfma_f32_16x16x32_bf16 v[2:5], v[138:141], v[184:187], 0
	v_mfma_f32_16x16x32_bf16 v[62:65], v[134:137], v[150:153], v[62:65]
	v_mfma_f32_16x16x32_bf16 v[10:13], v[142:145], v[150:153], v[10:13]
	v_mfma_f32_16x16x32_bf16 v[58:61], v[134:137], v[172:175], v[58:61]
	v_mfma_f32_16x16x32_bf16 v[14:17], v[142:145], v[172:175], v[14:17]
	v_mfma_f32_16x16x32_bf16 v[54:57], v[134:137], v[180:183], v[54:57]
	v_mfma_f32_16x16x32_bf16 v[6:9], v[142:145], v[180:183], v[6:9]
	v_mfma_f32_16x16x32_bf16 v[42:45], v[134:137], v[190:193], v[42:45]
	v_mfma_f32_16x16x32_bf16 v[2:5], v[142:145], v[190:193], v[2:5]
	s_barrier
	s_add_u32 s6, s90, 0x40000
	s_addc_u32 s7, s91, 0
	s_add_i32 m0, s39, 0x14000
	s_nop 0
	global_load_lds_dwordx4 v160, s[6:7]
	s_add_i32 m0, s39, 0x16000
	s_nop 0
	global_load_lds_dwordx4 v156, s[6:7]
	ds_read_b128 v[130:133], v189 offset:32768
	ds_read_b128 v[134:137], v189 offset:33792
	ds_read_b128 v[138:141], v189 offset:34816
	ds_read_b128 v[142:145], v189 offset:35840
	s_waitcnt vmcnt(6)
	s_barrier
	v_mfma_f32_16x16x32_bf16 v[50:53], v[194:197], v[146:149], 0
	v_mfma_f32_16x16x32_bf16 v[26:29], v[202:205], v[146:149], 0
	v_mfma_f32_16x16x32_bf16 v[46:49], v[194:197], v[168:171], 0
	v_mfma_f32_16x16x32_bf16 v[30:33], v[202:205], v[168:171], 0
	v_mfma_f32_16x16x32_bf16 v[38:41], v[194:197], v[176:179], 0
	v_mfma_f32_16x16x32_bf16 v[22:25], v[202:205], v[176:179], 0
	v_mfma_f32_16x16x32_bf16 v[34:37], v[194:197], v[184:187], 0
	v_mfma_f32_16x16x32_bf16 v[18:21], v[202:205], v[184:187], 0
	v_mfma_f32_16x16x32_bf16 v[50:53], v[198:201], v[150:153], v[50:53]
	v_mfma_f32_16x16x32_bf16 v[26:29], v[206:209], v[150:153], v[26:29]
	v_mfma_f32_16x16x32_bf16 v[46:49], v[198:201], v[172:175], v[46:49]
	v_mfma_f32_16x16x32_bf16 v[30:33], v[206:209], v[172:175], v[30:33]
	v_mfma_f32_16x16x32_bf16 v[38:41], v[198:201], v[180:183], v[38:41]
	v_mfma_f32_16x16x32_bf16 v[22:25], v[206:209], v[180:183], v[22:25]
	v_mfma_f32_16x16x32_bf16 v[34:37], v[198:201], v[190:193], v[34:37]
	v_mfma_f32_16x16x32_bf16 v[18:21], v[206:209], v[190:193], v[18:21]
	s_barrier
	s_add_u32 s6, s92, 0x40000
	s_addc_u32 s7, s93, 0
	s_mov_b32 m0, s61
	ds_read_b128 v[146:149], v253 offset:32768
	ds_read_b128 v[150:153], v253 offset:33792
	ds_read_b128 v[168:171], v253 offset:34816
	ds_read_b128 v[172:175], v253 offset:35840
	ds_read_b128 v[176:179], v253 offset:36864
	ds_read_b128 v[180:183], v253 offset:37888
	ds_read_b128 v[184:187], v253 offset:38912
	global_load_lds_dwordx4 v162, s[6:7]
	s_mov_b32 m0, s72
	ds_read_b128 v[190:193], v253 offset:39936
	global_load_lds_dwordx4 v158, s[6:7]
	s_waitcnt lgkmcnt(8)
	s_barrier
	s_waitcnt lgkmcnt(0)
	v_mfma_f32_16x16x32_bf16 v[126:129], v[130:133], v[146:149], v[126:129]
	v_mfma_f32_16x16x32_bf16 v[70:73], v[138:141], v[146:149], v[70:73]
	v_mfma_f32_16x16x32_bf16 v[122:125], v[130:133], v[168:171], v[122:125]
	v_mfma_f32_16x16x32_bf16 v[74:77], v[138:141], v[168:171], v[74:77]
	v_mfma_f32_16x16x32_bf16 v[114:117], v[130:133], v[176:179], v[114:117]
	v_mfma_f32_16x16x32_bf16 v[66:69], v[138:141], v[176:179], v[66:69]
	v_mfma_f32_16x16x32_bf16 v[110:113], v[130:133], v[184:187], v[110:113]
	v_mfma_f32_16x16x32_bf16 v[78:81], v[138:141], v[184:187], v[78:81]
	v_mfma_f32_16x16x32_bf16 v[126:129], v[134:137], v[150:153], v[126:129]
	v_mfma_f32_16x16x32_bf16 v[70:73], v[142:145], v[150:153], v[70:73]
	v_mfma_f32_16x16x32_bf16 v[122:125], v[134:137], v[172:175], v[122:125]
	v_mfma_f32_16x16x32_bf16 v[74:77], v[142:145], v[172:175], v[74:77]
	v_mfma_f32_16x16x32_bf16 v[114:117], v[134:137], v[180:183], v[114:117]
	v_mfma_f32_16x16x32_bf16 v[66:69], v[142:145], v[180:183], v[66:69]
	v_mfma_f32_16x16x32_bf16 v[110:113], v[134:137], v[190:193], v[110:113]
	v_mfma_f32_16x16x32_bf16 v[78:81], v[142:145], v[190:193], v[78:81]
	s_barrier
	s_add_i32 m0, s39, 0x18000
	ds_read_b128 v[194:197], v189 offset:49152
	ds_read_b128 v[198:201], v189 offset:50176
	ds_read_b128 v[202:205], v189 offset:51200
	ds_read_b128 v[206:209], v189 offset:52224
	s_add_u32 s98, s90, s40
	s_addc_u32 s99, s91, s41
	global_load_lds_dwordx4 v160, s[98:99]
	s_add_i32 m0, s39, 0x1a000
	s_nop 0
	global_load_lds_dwordx4 v156, s[98:99]
	s_barrier
	s_waitcnt lgkmcnt(0)
	v_mfma_f32_16x16x32_bf16 v[118:121], v[194:197], v[146:149], v[118:121]
	v_mfma_f32_16x16x32_bf16 v[94:97], v[202:205], v[146:149], v[94:97]
	v_mfma_f32_16x16x32_bf16 v[106:109], v[194:197], v[168:171], v[106:109]
	v_mfma_f32_16x16x32_bf16 v[90:93], v[202:205], v[168:171], v[90:93]
	v_mfma_f32_16x16x32_bf16 v[102:105], v[194:197], v[176:179], v[102:105]
	v_mfma_f32_16x16x32_bf16 v[82:85], v[202:205], v[176:179], v[82:85]
	v_mfma_f32_16x16x32_bf16 v[98:101], v[194:197], v[184:187], v[98:101]
	v_mfma_f32_16x16x32_bf16 v[86:89], v[202:205], v[184:187], v[86:89]
	v_mfma_f32_16x16x32_bf16 v[118:121], v[198:201], v[150:153], v[118:121]
	v_mfma_f32_16x16x32_bf16 v[94:97], v[206:209], v[150:153], v[94:97]
	v_mfma_f32_16x16x32_bf16 v[106:109], v[198:201], v[172:175], v[106:109]
	v_mfma_f32_16x16x32_bf16 v[90:93], v[206:209], v[172:175], v[90:93]
	v_mfma_f32_16x16x32_bf16 v[102:105], v[198:201], v[180:183], v[102:105]
	v_mfma_f32_16x16x32_bf16 v[82:85], v[206:209], v[180:183], v[82:85]
	v_mfma_f32_16x16x32_bf16 v[98:101], v[198:201], v[190:193], v[98:101]
	v_mfma_f32_16x16x32_bf16 v[86:89], v[206:209], v[190:193], v[86:89]
	s_mov_b32 m0, s95
	s_barrier
	ds_read_b128 v[146:149], v253 offset:49152
	ds_read_b128 v[150:153], v253 offset:50176
	ds_read_b128 v[168:171], v253 offset:51200
	ds_read_b128 v[172:175], v253 offset:52224
	ds_read_b128 v[176:179], v253 offset:53248
	ds_read_b128 v[180:183], v253 offset:54272
	ds_read_b128 v[184:187], v253 offset:55296
	ds_read_b128 v[190:193], v253 offset:56320
	s_add_u32 s98, s100, s40
	s_addc_u32 s99, s101, s41
	global_load_lds_dwordx4 v162, s[98:99]
	s_mov_b32 m0, s96
	s_nop 0
	global_load_lds_dwordx4 v158, s[98:99]
	s_waitcnt vmcnt(10)
	s_barrier
	s_waitcnt lgkmcnt(0)
	v_mfma_f32_16x16x32_bf16 v[62:65], v[130:133], v[146:149], v[62:65]
	v_mfma_f32_16x16x32_bf16 v[10:13], v[138:141], v[146:149], v[10:13]
	v_mfma_f32_16x16x32_bf16 v[58:61], v[130:133], v[168:171], v[58:61]
	v_mfma_f32_16x16x32_bf16 v[14:17], v[138:141], v[168:171], v[14:17]
	v_mfma_f32_16x16x32_bf16 v[54:57], v[130:133], v[176:179], v[54:57]
	v_mfma_f32_16x16x32_bf16 v[6:9], v[138:141], v[176:179], v[6:9]
	v_mfma_f32_16x16x32_bf16 v[42:45], v[130:133], v[184:187], v[42:45]
	v_mfma_f32_16x16x32_bf16 v[2:5], v[138:141], v[184:187], v[2:5]
	v_mfma_f32_16x16x32_bf16 v[62:65], v[134:137], v[150:153], v[62:65]
	v_mfma_f32_16x16x32_bf16 v[10:13], v[142:145], v[150:153], v[10:13]
	v_mfma_f32_16x16x32_bf16 v[58:61], v[134:137], v[172:175], v[58:61]
	v_mfma_f32_16x16x32_bf16 v[14:17], v[142:145], v[172:175], v[14:17]
	v_mfma_f32_16x16x32_bf16 v[54:57], v[134:137], v[180:183], v[54:57]
	v_mfma_f32_16x16x32_bf16 v[6:9], v[142:145], v[180:183], v[6:9]
	v_mfma_f32_16x16x32_bf16 v[42:45], v[134:137], v[190:193], v[42:45]
	v_mfma_f32_16x16x32_bf16 v[2:5], v[142:145], v[190:193], v[2:5]
	s_barrier
	s_add_u32 s6, s90, 0x40080
	s_addc_u32 s7, s91, 0
	s_add_i32 m0, s39, 0x1c000
	s_nop 0
	global_load_lds_dwordx4 v160, s[6:7]
	s_add_i32 m0, s39, 0x1e000
	s_nop 0
	global_load_lds_dwordx4 v156, s[6:7]
	ds_read_b128 v[130:133], v189
	ds_read_b128 v[134:137], v189 offset:1024
	ds_read_b128 v[138:141], v189 offset:2048
	ds_read_b128 v[142:145], v189 offset:3072
	s_waitcnt vmcnt(6)
	s_barrier
	v_mfma_f32_16x16x32_bf16 v[50:53], v[194:197], v[146:149], v[50:53]
	v_mfma_f32_16x16x32_bf16 v[26:29], v[202:205], v[146:149], v[26:29]
	v_mfma_f32_16x16x32_bf16 v[46:49], v[194:197], v[168:171], v[46:49]
	v_mfma_f32_16x16x32_bf16 v[30:33], v[202:205], v[168:171], v[30:33]
	v_mfma_f32_16x16x32_bf16 v[38:41], v[194:197], v[176:179], v[38:41]
	v_mfma_f32_16x16x32_bf16 v[22:25], v[202:205], v[176:179], v[22:25]
	v_mfma_f32_16x16x32_bf16 v[34:37], v[194:197], v[184:187], v[34:37]
	v_mfma_f32_16x16x32_bf16 v[18:21], v[202:205], v[184:187], v[18:21]
	v_mfma_f32_16x16x32_bf16 v[50:53], v[198:201], v[150:153], v[50:53]
	v_mfma_f32_16x16x32_bf16 v[26:29], v[206:209], v[150:153], v[26:29]
	v_mfma_f32_16x16x32_bf16 v[46:49], v[198:201], v[172:175], v[46:49]
	v_mfma_f32_16x16x32_bf16 v[30:33], v[206:209], v[172:175], v[30:33]
	v_mfma_f32_16x16x32_bf16 v[38:41], v[198:201], v[180:183], v[38:41]
	v_mfma_f32_16x16x32_bf16 v[22:25], v[206:209], v[180:183], v[22:25]
	v_mfma_f32_16x16x32_bf16 v[34:37], v[198:201], v[190:193], v[34:37]
	v_mfma_f32_16x16x32_bf16 v[18:21], v[206:209], v[190:193], v[18:21]
	s_add_i32 s45, s45, 2
	s_add_u32 s28, s28, 0x100
	s_addc_u32 s29, s29, 0
	s_mov_b64 s[6:7], s[88:89]
	s_add_u32 s88, s6, 0x100
	s_addc_u32 s89, s7, 0
	s_cmp_eq_u32 s45, 12
	s_cselect_b32 s93, s17, s89
	s_cselect_b32 s92, s22, s88
	s_cselect_b32 s91, s15, s29
	s_cselect_b32 s90, s23, s28
	s_cmp_gt_u32 s45, 13
	s_barrier
	.p2align 3
	s_nop 0
